# attention: dropped v_max(x,x) canonicalisations in score-max trees (14 VALU per wave-tile)
# speedup vs baseline: 1.0273x; 1.0056x over previous
; #define LAS __attribute__((address_space(3)))
; #define MFMA32(a, b, c) __builtin_amdgcn_mfma_f32_32x32x16_bf16((a), (b), (c), 0, 0, 0)
; #define AT_LMAX(P, MX) do { MX = fmaxf(fmaxf(P[0], P[1]), fmaxf(P[2], P[3])); \
;         _Pragma("unroll") for (int i_ = 4; i_ < 16; i_ += 4) MX = fmaxf(fmaxf(MX, P[i_]), fmaxf(fmaxf(P[i_ + 1], P[i_ + 2]), P[i_ + 3])); } while (0)
; __device__ __forceinline__ void attn_unit(LAS unsigned char* lds, const GAS bf16_t* __restrict__ QR, const GAS float* __restrict__ ssq, const GAS float* __restrict__ RT, const GAS bf16_t* __restrict__ K, const GAS bf16_t* __restrict__ Vt, GAS bf16_t* __restrict__ A2, int b, int h, int qb, int tid, i ...
;     ...
;             const LAS unsigned char* kb = sb + (32 * hh + r32s) * AT_KROW + hi * 16;
;             f32x16 pA, pB;
; #pragma unroll
;             for (int i = 0; i < 16; ++i) { pA[i] = 0.f; pB[i] = 0.f; }
; #pragma unroll
;             for (int d0 = 0; d0 < 6; ++d0) { const bf16x8 a0 = *(const LAS bf16x8*)(kb + d0 * 32); pA = MFMA32(a0, qa[d0], pA); pB = MFMA32(a0, qc[d0], pB); }
;             u32x4 pwA0, pwA1, pwB0, pwB1;
;             float mxA, mxB; AT_LMAX(pA, mxA); AT_LMAX(pB, mxB);
;             { const float oa = __shfl_xor(mxA, 32), ob = __shfl_xor(mxB, 32); mxA = fmaxf(mxA, oa); mxB = fmaxf(mxB, ob); }
;             AT_SOFTMAX(pA, mxA, mA, lA, oA0, oA1, pwA0, pwA1);
;             AT_SOFTMAX(pB, mxB, mB, lB, oB0, oB1, pwB0, pwB1);
.LBB0_139:
	s_mul_i32 s22, s1, 0x5800
	s_add_i32 s24, s22, 0
	v_add_u32_e32 v66, s24, v154
	v_add_u32_e32 v212, v66, v207
	ds_read_b128 v[66:69], v212
	ds_read_b128 v[214:217], v212 offset:32
	ds_read_b128 v[218:221], v212 offset:64
	ds_read_b128 v[222:225], v212 offset:96
	ds_read_b128 v[226:229], v212 offset:128
	ds_read_b128 v[230:233], v212 offset:160
	s_waitcnt lgkmcnt(5)
	v_mfma_f32_32x32x16_bf16 v[82:97], v[66:69], v[98:101], v[188:203]
	v_mfma_f32_32x32x16_bf16 v[66:81], v[66:69], v[118:121], v[234:249]
	s_waitcnt lgkmcnt(4)
	v_mfma_f32_32x32x16_bf16 v[82:97], v[214:217], v[102:105], v[82:97]
	v_mfma_f32_32x32x16_bf16 v[66:81], v[214:217], v[122:125], v[66:81]
	s_waitcnt lgkmcnt(3)
	v_mfma_f32_32x32x16_bf16 v[82:97], v[218:221], v[106:109], v[82:97]
	v_mfma_f32_32x32x16_bf16 v[66:81], v[218:221], v[126:129], v[66:81]
	s_waitcnt lgkmcnt(2)
	v_mfma_f32_32x32x16_bf16 v[82:97], v[222:225], v[110:113], v[82:97]
	v_mfma_f32_32x32x16_bf16 v[66:81], v[222:225], v[130:133], v[66:81]
	s_waitcnt lgkmcnt(1)
	v_mfma_f32_32x32x16_bf16 v[82:97], v[226:229], v[134:137], v[82:97]
	v_mfma_f32_32x32x16_bf16 v[66:81], v[226:229], v[138:141], v[66:81]
	s_waitcnt lgkmcnt(0)
	v_mfma_f32_32x32x16_bf16 v[82:97], v[230:233], v[114:117], v[82:97]
	v_mfma_f32_32x32x16_bf16 v[66:81], v[230:233], v[142:145], v[66:81]
	s_nop 10
	v_max_f32_e32 v210, v84, v85
	v_max3_f32 v210, v82, v83, v210
	v_max3_f32 v213, v87, v88, v89
	v_max3_f32 v214, v91, v92, v93
	v_max3_f32 v210, v210, v86, v213
	v_max3_f32 v215, v95, v96, v97
	v_max_f32_e32 v216, v68, v69
	v_max3_f32 v210, v210, v90, v214
	v_max3_f32 v216, v66, v67, v216
	v_max3_f32 v217, v71, v72, v73
	v_max3_f32 v214, v210, v94, v215
	v_max3_f32 v216, v216, v70, v217
	v_max3_f32 v217, v75, v76, v77
	ds_bpermute_b32 v215, v153, v214
	v_max3_f32 v210, v216, v74, v217
	v_max3_f32 v213, v79, v80, v81
	v_max3_f32 v210, v210, v78, v213
	ds_bpermute_b32 v213, v153, v210
	s_waitcnt lgkmcnt(1)
	v_max_f32_e32 v214, v214, v215
	v_cmp_lt_f32_e32 vcc, s100, v214
	s_cbranch_vccz .LBB0_141
	v_max_f32_e32 v215, s101, v214
	v_max_f32_e32 v214, 0, v215
	v_exp_f32_e64 v214, -v214
	v_sub_f32_e32 v188, v188, v215
	v_sub_f32_e32 v189, v189, v215
	v_sub_f32_e32 v190, v190, v215
	v_sub_f32_e32 v191, v191, v215
	v_sub_f32_e32 v192, v192, v215
	v_sub_f32_e32 v193, v193, v215
	v_sub_f32_e32 v194, v194, v215
	v_sub_f32_e32 v195, v195, v215
	v_sub_f32_e32 v196, v196, v215
	v_sub_f32_e32 v197, v197, v215
	v_sub_f32_e32 v198, v198, v215
	v_sub_f32_e32 v199, v199, v215
	v_sub_f32_e32 v200, v200, v215
	v_sub_f32_e32 v201, v201, v215
	v_sub_f32_e32 v202, v202, v215
	v_sub_f32_e32 v203, v203, v215
	v_sub_f32_e32 v82, v82, v215
	v_sub_f32_e32 v83, v83, v215
	v_sub_f32_e32 v84, v84, v215
	v_sub_f32_e32 v85, v85, v215
	v_sub_f32_e32 v86, v86, v215
	v_sub_f32_e32 v87, v87, v215
	v_sub_f32_e32 v88, v88, v215
	v_sub_f32_e32 v89, v89, v215
	v_sub_f32_e32 v90, v90, v215
	v_sub_f32_e32 v91, v91, v215
	v_sub_f32_e32 v92, v92, v215
	v_sub_f32_e32 v93, v93, v215
	v_sub_f32_e32 v94, v94, v215
	v_sub_f32_e32 v95, v95, v215
	v_sub_f32_e32 v96, v96, v215
	v_sub_f32_e32 v97, v97, v215
	v_pk_mul_f32 v[64:65], v[64:65], v[214:215] op_sel_hi:[1,0]
	v_pk_mul_f32 v[62:63], v[62:63], v[214:215] op_sel_hi:[1,0]
	v_pk_mul_f32 v[60:61], v[60:61], v[214:215] op_sel_hi:[1,0]
	v_pk_mul_f32 v[58:59], v[58:59], v[214:215] op_sel_hi:[1,0]
	v_pk_mul_f32 v[56:57], v[56:57], v[214:215] op_sel_hi:[1,0]
	v_pk_mul_f32 v[54:55], v[54:55], v[214:215] op_sel_hi:[1,0]
	v_pk_mul_f32 v[52:53], v[52:53], v[214:215] op_sel_hi:[1,0]
	v_pk_mul_f32 v[50:51], v[50:51], v[214:215] op_sel_hi:[1,0]
	v_pk_mul_f32 v[48:49], v[48:49], v[214:215] op_sel_hi:[1,0]
	v_pk_mul_f32 v[46:47], v[46:47], v[214:215] op_sel_hi:[1,0]
	v_pk_mul_f32 v[44:45], v[44:45], v[214:215] op_sel_hi:[1,0]
	v_pk_mul_f32 v[42:43], v[42:43], v[214:215] op_sel_hi:[1,0]
	v_pk_mul_f32 v[40:41], v[40:41], v[214:215] op_sel_hi:[1,0]
	v_pk_mul_f32 v[38:39], v[38:39], v[214:215] op_sel_hi:[1,0]
	v_pk_mul_f32 v[36:37], v[36:37], v[214:215] op_sel_hi:[1,0]
	v_pk_mul_f32 v[34:35], v[34:35], v[214:215] op_sel_hi:[1,0]
	v_mul_f32_e32 v211, v211, v214
.LBB0_141:
	s_waitcnt lgkmcnt(0)
	v_max_f32_e32 v210, v210, v213
	v_cmp_lt_f32_e32 vcc, s100, v210
	s_cbranch_vccz .LBB0_143
	v_max_f32_e32 v213, s101, v210
	v_max_f32_e32 v210, 0, v213
	v_exp_f32_e64 v210, -v210
	v_sub_f32_e32 v234, v234, v213
	v_sub_f32_e32 v235, v235, v213
	v_sub_f32_e32 v236, v236, v213
	v_sub_f32_e32 v237, v237, v213
	v_sub_f32_e32 v238, v238, v213
	v_sub_f32_e32 v239, v239, v213
	v_sub_f32_e32 v240, v240, v213
	v_sub_f32_e32 v241, v241, v213
	v_sub_f32_e32 v242, v242, v213
	v_sub_f32_e32 v243, v243, v213
	v_sub_f32_e32 v244, v244, v213
	v_sub_f32_e32 v245, v245, v213
	v_sub_f32_e32 v246, v246, v213
	v_sub_f32_e32 v247, v247, v213
	v_sub_f32_e32 v248, v248, v213
	v_sub_f32_e32 v249, v249, v213
	v_sub_f32_e32 v66, v66, v213
	v_sub_f32_e32 v67, v67, v213
	v_sub_f32_e32 v68, v68, v213
	v_sub_f32_e32 v69, v69, v213
	v_sub_f32_e32 v70, v70, v213
	v_sub_f32_e32 v71, v71, v213
	v_sub_f32_e32 v72, v72, v213
	v_sub_f32_e32 v73, v73, v213
	v_sub_f32_e32 v74, v74, v213
	v_sub_f32_e32 v75, v75, v213
	v_sub_f32_e32 v76, v76, v213
	v_sub_f32_e32 v77, v77, v213
	v_sub_f32_e32 v78, v78, v213
	v_sub_f32_e32 v79, v79, v213
	v_sub_f32_e32 v80, v80, v213
	v_sub_f32_e32 v81, v81, v213
	v_pk_mul_f32 v[32:33], v[32:33], v[210:211] op_sel_hi:[1,0]
	v_pk_mul_f32 v[30:31], v[30:31], v[210:211] op_sel_hi:[1,0]
	v_pk_mul_f32 v[28:29], v[28:29], v[210:211] op_sel_hi:[1,0]
	v_pk_mul_f32 v[26:27], v[26:27], v[210:211] op_sel_hi:[1,0]
	v_pk_mul_f32 v[24:25], v[24:25], v[210:211] op_sel_hi:[1,0]
	v_pk_mul_f32 v[22:23], v[22:23], v[210:211] op_sel_hi:[1,0]
	v_pk_mul_f32 v[20:21], v[20:21], v[210:211] op_sel_hi:[1,0]
	v_pk_mul_f32 v[18:19], v[18:19], v[210:211] op_sel_hi:[1,0]
	v_pk_mul_f32 v[16:17], v[16:17], v[210:211] op_sel_hi:[1,0]
	v_pk_mul_f32 v[14:15], v[14:15], v[210:211] op_sel_hi:[1,0]
	v_pk_mul_f32 v[12:13], v[12:13], v[210:211] op_sel_hi:[1,0]
	v_pk_mul_f32 v[10:11], v[10:11], v[210:211] op_sel_hi:[1,0]
	v_pk_mul_f32 v[8:9], v[8:9], v[210:211] op_sel_hi:[1,0]
	v_pk_mul_f32 v[6:7], v[6:7], v[210:211] op_sel_hi:[1,0]
	v_pk_mul_f32 v[4:5], v[4:5], v[210:211] op_sel_hi:[1,0]
	v_pk_mul_f32 v[2:3], v[2:3], v[210:211] op_sel_hi:[1,0]
	v_mul_f32_e32 v209, v209, v210
; #define LAS __attribute__((address_space(3)))
; #define MFMA32(a, b, c) __builtin_amdgcn_mfma_f32_32x32x16_bf16((a), (b), (c), 0, 0, 0)
; #define AT_LMAX(P, MX) do { MX = fmaxf(fmaxf(P[0], P[1]), fmaxf(P[2], P[3])); \
;         _Pragma("unroll") for (int i_ = 4; i_ < 16; i_ += 4) MX = fmaxf(fmaxf(MX, P[i_]), fmaxf(fmaxf(P[i_ + 1], P[i_ + 2]), P[i_ + 3])); } while (0)
; __device__ __forceinline__ void attn_unit(LAS unsigned char* lds, const GAS bf16_t* __restrict__ QR, const GAS float* __restrict__ ssq, const GAS float* __restrict__ RT, const GAS bf16_t* __restrict__ K, const GAS bf16_t* __restrict__ Vt, GAS bf16_t* __restrict__ A2, int b, int h, int qb, int tid, i ...
;     ...
;             for (int d0 = 0; d0 < 6; ++d0) { const bf16x8 a0 = *(const LAS bf16x8*)(kb + d0 * 32); pA = MFMA32(a0, qa[d0], pA); pB = MFMA32(a0, qc[d0], pB); }
;             u32x4 pwA0, pwA1, pwB0, pwB1;
;             float mxA, mxB; AT_LMAX(pA, mxA); AT_LMAX(pB, mxB);
;             { const float oa = __shfl_xor(mxA, 32), ob = __shfl_xor(mxB, 32); mxA = fmaxf(mxA, oa); mxB = fmaxf(mxB, ob); }
;             AT_SOFTMAX(pA, mxA, mA, lA, oA0, oA1, pwA0, pwA1);
;             AT_SOFTMAX(pB, mxB, mB, lB, oB0, oB1, pwB0, pwB1);
;             const LAS unsigned char* vb = sb + AT_VOFF + r32 * AT_VROW + hi * 16 + hh * 64;
; #pragma unroll
;             for (int ks = 0; ks < 2; ++ks) {
;                 const bf16x8 va0 = *(const LAS bf16x8*)(vb + ks * 32), va1 = *(const LAS bf16x8*)(vb + 32 * AT_VROW + ks * 32);
;                 const bf16x8 pa = __builtin_bit_cast(bf16x8, ks ? pwA1 : pwA0), pb = __builtin_bit_cast(bf16x8, ks ? pwB1 : pwB0);
;                 oA0 = MFMA32(va0, pa, oA0); oA1 = MFMA32(va1, pa, oA1); oB0 = MFMA32(va0, pb, oB0); oB1 = MFMA32(va1, pb, oB1);
.LBB0_143:
	s_mov_b32 s100, 0x41000000
	s_mov_b32 s101, 0
	v_exp_f32_e32 v210, v82
	v_exp_f32_e32 v213, v83
	v_exp_f32_e32 v214, v84
	v_exp_f32_e32 v215, v85
	v_exp_f32_e32 v216, v86
	v_exp_f32_e32 v217, v87
	v_exp_f32_e32 v218, v88
	v_exp_f32_e32 v219, v89
	v_cvt_pk_bf16_f32 v86, v210, v213
	v_exp_f32_e32 v90, v90
	v_add_f32_e32 v210, v213, v210
	v_exp_f32_e32 v91, v91
	v_add_f32_e32 v210, v214, v210
	v_exp_f32_e32 v92, v92
	v_add_f32_e32 v210, v215, v210
	v_exp_f32_e32 v93, v93
	v_add_f32_e32 v210, v216, v210
	v_exp_f32_e32 v213, v66
	v_exp_f32_e32 v94, v94
	v_cvt_pk_bf16_f32 v87, v214, v215
	v_add_f32_e32 v210, v217, v210
	v_exp_f32_e32 v214, v67
	v_exp_f32_e32 v95, v95
	v_add_f32_e32 v210, v218, v210
	v_exp_f32_e32 v215, v68
	v_exp_f32_e32 v96, v96
	v_cvt_pk_bf16_f32 v88, v216, v217
	v_add_f32_e32 v210, v219, v210
	v_exp_f32_e32 v216, v69
	v_exp_f32_e32 v97, v97
	v_cvt_pk_bf16_f32 v82, v90, v91
	v_add_f32_e32 v90, v90, v210
	v_exp_f32_e32 v217, v70
	v_cvt_pk_bf16_f32 v89, v218, v219
	v_add_f32_e32 v90, v91, v90
	v_exp_f32_e32 v218, v71
	v_add_f32_e32 v90, v92, v90
	v_exp_f32_e32 v219, v72
	v_add_f32_e32 v90, v93, v90
	v_exp_f32_e32 v220, v73
	v_add_f32_e32 v90, v94, v90
	v_exp_f32_e32 v221, v74
	v_add_f32_e32 v90, v95, v90
	v_exp_f32_e32 v222, v75
	v_add_f32_e32 v90, v96, v90
	v_exp_f32_e32 v223, v76
	v_add_f32_e32 v90, v97, v90
	v_exp_f32_e32 v224, v77
	v_add_f32_e32 v211, v211, v90
	v_add_u32_e32 v90, s24, v155
	v_exp_f32_e32 v225, v78
	v_exp_f32_e32 v226, v79
	v_add_u32_e32 v210, v90, v154
	v_cvt_pk_bf16_f32 v83, v92, v93
	v_exp_f32_e32 v227, v80
	v_exp_f32_e32 v228, v81
	ds_read_b128 v[74:77], v210 offset:17920
	ds_read_b128 v[78:81], v210 offset:13312
	ds_read_b128 v[90:93], v210 offset:13344
	v_cvt_pk_bf16_f32 v70, v213, v214
	v_cvt_pk_bf16_f32 v71, v215, v216
	v_cvt_pk_bf16_f32 v72, v217, v218
	v_cvt_pk_bf16_f32 v73, v219, v220
	s_waitcnt lgkmcnt(1)
	v_mfma_f32_32x32x16_bf16 v[50:65], v[78:81], v[86:89], v[50:65]
	v_cvt_pk_bf16_f32 v84, v94, v95
	v_cvt_pk_bf16_f32 v85, v96, v97
	v_cvt_pk_bf16_f32 v66, v221, v222
	v_cvt_pk_bf16_f32 v67, v223, v224
	v_cvt_pk_bf16_f32 v68, v225, v226
	v_cvt_pk_bf16_f32 v69, v227, v228
	v_mfma_f32_32x32x16_bf16 v[18:33], v[78:81], v[70:73], v[18:33]
	v_mfma_f32_32x32x16_bf16 v[2:17], v[74:77], v[70:73], v[2:17]
	v_add_f32_e32 v213, v214, v213
	v_add_f32_e32 v213, v215, v213
	v_add_f32_e32 v213, v216, v213
	v_add_f32_e32 v213, v217, v213
	v_add_f32_e32 v213, v218, v213
	v_add_f32_e32 v213, v219, v213
	v_add_f32_e32 v213, v220, v213
	v_add_f32_e32 v213, v221, v213
	v_add_f32_e32 v213, v222, v213
	v_add_f32_e32 v213, v223, v213
	v_add_f32_e32 v213, v224, v213
	v_add_f32_e32 v213, v225, v213
	v_add_f32_e32 v213, v226, v213
	v_add_f32_e32 v213, v227, v213
	v_add_f32_e32 v213, v228, v213
	v_add_f32_e32 v209, v209, v213
	ds_read_b128 v[70:73], v210 offset:17952
	v_mfma_f32_32x32x16_bf16 v[34:49], v[74:77], v[86:89], v[34:49]
	s_waitcnt lgkmcnt(1)
	v_mfma_f32_32x32x16_bf16 v[50:65], v[90:93], v[82:85], v[50:65]
	s_waitcnt lgkmcnt(0)
	v_mfma_f32_32x32x16_bf16 v[34:49], v[70:73], v[82:85], v[34:49]
	ds_read_b128 v[82:85], v212 offset:6656
	ds_read_b128 v[230:233], v212 offset:6688
	ds_read_b128 v[214:217], v212 offset:6720
	ds_read_b128 v[218:221], v212 offset:6752
	ds_read_b128 v[222:225], v212 offset:6784
	ds_read_b128 v[226:229], v212 offset:6816
	v_mfma_f32_32x32x16_bf16 v[18:33], v[90:93], v[66:69], v[18:33]
	v_mfma_f32_32x32x16_bf16 v[2:17], v[70:73], v[66:69], v[2:17]
	s_waitcnt lgkmcnt(5)
	v_mfma_f32_32x32x16_bf16 v[66:81], v[82:85], v[98:101], v[188:203]
	s_waitcnt lgkmcnt(4)
	v_mfma_f32_32x32x16_bf16 v[66:81], v[230:233], v[102:105], v[66:81]
	s_waitcnt lgkmcnt(3)
	v_mfma_f32_32x32x16_bf16 v[66:81], v[214:217], v[106:109], v[66:81]
	s_waitcnt lgkmcnt(2)
	v_mfma_f32_32x32x16_bf16 v[66:81], v[218:221], v[110:113], v[66:81]
	s_waitcnt lgkmcnt(1)
	v_mfma_f32_32x32x16_bf16 v[66:81], v[222:225], v[134:137], v[66:81]
	s_waitcnt lgkmcnt(0)
	v_mfma_f32_32x32x16_bf16 v[66:81], v[226:229], v[114:117], v[66:81]
	s_nop 11
	v_max_f32_e32 v86, v68, v69
	v_max3_f32 v179, v66, v67, v86
	v_mfma_f32_32x32x16_bf16 v[82:97], v[82:85], v[118:121], v[234:249]
	v_max3_f32 v250, v71, v72, v73
	v_max3_f32 v251, v75, v76, v77
	v_max3_f32 v179, v179, v70, v250
	v_max3_f32 v252, v79, v80, v81
	v_max3_f32 v179, v179, v74, v251
	v_mfma_f32_32x32x16_bf16 v[82:97], v[230:233], v[122:125], v[82:97]
	v_mfma_f32_32x32x16_bf16 v[82:97], v[214:217], v[126:129], v[82:97]
	v_mfma_f32_32x32x16_bf16 v[82:97], v[218:221], v[130:133], v[82:97]
	v_mfma_f32_32x32x16_bf16 v[82:97], v[222:225], v[138:141], v[82:97]
	v_mfma_f32_32x32x16_bf16 v[82:97], v[226:229], v[142:145], v[82:97]
	s_nop 11
	v_max_f32_e32 v212, v84, v85
	v_max3_f32 v212, v82, v83, v212
	v_max3_f32 v230, v87, v88, v89
	v_max3_f32 v212, v212, v86, v230
	v_max3_f32 v230, v91, v92, v93
	v_max3_f32 v212, v212, v90, v230
	v_max3_f32 v230, v95, v96, v97
	v_max3_f32 v212, v212, v94, v230
	v_max3_f32 v230, v179, v78, v252
	ds_bpermute_b32 v231, v153, v230
	ds_bpermute_b32 v179, v153, v212
	s_waitcnt lgkmcnt(1)
	v_max_f32_e32 v230, v230, v231
	v_cmp_lt_f32_e32 vcc, s100, v230
	s_cbranch_vccz .LBB0_145
; __device__ __forceinline__ void attn_unit(LAS unsigned char* lds, const GAS bf16_t* __restrict__ QR, const GAS float* __restrict__ ssq, const GAS float* __restrict__ RT, const GAS bf16_t* __restrict__ K, const GAS bf16_t* __restrict__ Vt, GAS bf16_t* __restrict__ A2, int b, int h, int qb, int tid, i ...
;     ...
;             { const float oa = __shfl_xor(mxA, 32), ob = __shfl_xor(mxB, 32); mxA = fmaxf(mxA, oa); mxB = fmaxf(mxB, ob); }
;             AT_SOFTMAX(pA, mxA, mA, lA, oA0, oA1, pwA0, pwA1);
;             AT_SOFTMAX(pB, mxB, mB, lB, oB0, oB1, pwB0, pwB1);
	v_max_f32_e32 v231, s101, v230
	v_max_f32_e32 v230, 0, v231
	v_exp_f32_e64 v230, -v230
	v_sub_f32_e32 v188, v188, v231
	v_sub_f32_e32 v189, v189, v231
	v_sub_f32_e32 v190, v190, v231
	v_sub_f32_e32 v191, v191, v231
	v_sub_f32_e32 v192, v192, v231
	v_sub_f32_e32 v193, v193, v231
	v_sub_f32_e32 v194, v194, v231
	v_sub_f32_e32 v195, v195, v231
	v_sub_f32_e32 v196, v196, v231
	v_sub_f32_e32 v197, v197, v231
	v_sub_f32_e32 v198, v198, v231
	v_sub_f32_e32 v199, v199, v231
	v_sub_f32_e32 v200, v200, v231
	v_sub_f32_e32 v201, v201, v231
	v_sub_f32_e32 v202, v202, v231
	v_sub_f32_e32 v203, v203, v231
	v_sub_f32_e32 v66, v66, v231
	v_sub_f32_e32 v67, v67, v231
	v_sub_f32_e32 v68, v68, v231
	v_sub_f32_e32 v69, v69, v231
	v_sub_f32_e32 v70, v70, v231
	v_sub_f32_e32 v71, v71, v231
	v_sub_f32_e32 v72, v72, v231
	v_sub_f32_e32 v73, v73, v231
	v_sub_f32_e32 v74, v74, v231
	v_sub_f32_e32 v75, v75, v231
	v_sub_f32_e32 v76, v76, v231
	v_sub_f32_e32 v77, v77, v231
	v_sub_f32_e32 v78, v78, v231
	v_sub_f32_e32 v79, v79, v231
	v_sub_f32_e32 v80, v80, v231
	v_sub_f32_e32 v81, v81, v231
	v_pk_mul_f32 v[64:65], v[64:65], v[230:231] op_sel_hi:[1,0]
	v_pk_mul_f32 v[62:63], v[62:63], v[230:231] op_sel_hi:[1,0]
	v_pk_mul_f32 v[60:61], v[60:61], v[230:231] op_sel_hi:[1,0]
	v_pk_mul_f32 v[58:59], v[58:59], v[230:231] op_sel_hi:[1,0]
	v_pk_mul_f32 v[56:57], v[56:57], v[230:231] op_sel_hi:[1,0]
	v_pk_mul_f32 v[54:55], v[54:55], v[230:231] op_sel_hi:[1,0]
	v_pk_mul_f32 v[52:53], v[52:53], v[230:231] op_sel_hi:[1,0]
	v_pk_mul_f32 v[50:51], v[50:51], v[230:231] op_sel_hi:[1,0]
	v_pk_mul_f32 v[48:49], v[48:49], v[230:231] op_sel_hi:[1,0]
	v_pk_mul_f32 v[46:47], v[46:47], v[230:231] op_sel_hi:[1,0]
	v_pk_mul_f32 v[44:45], v[44:45], v[230:231] op_sel_hi:[1,0]
	v_pk_mul_f32 v[42:43], v[42:43], v[230:231] op_sel_hi:[1,0]
	v_pk_mul_f32 v[40:41], v[40:41], v[230:231] op_sel_hi:[1,0]
	v_pk_mul_f32 v[38:39], v[38:39], v[230:231] op_sel_hi:[1,0]
	v_pk_mul_f32 v[36:37], v[36:37], v[230:231] op_sel_hi:[1,0]
	v_pk_mul_f32 v[34:35], v[34:35], v[230:231] op_sel_hi:[1,0]
	v_mul_f32_e32 v211, v211, v230
.LBB0_145:
	s_waitcnt lgkmcnt(0)
	v_max_f32_e32 v212, v212, v179
	v_cmp_lt_f32_e32 vcc, s100, v212
	s_cbranch_vccz .LBB0_134
	v_max_f32_e32 v213, s101, v212
	v_max_f32_e32 v212, 0, v213
	v_exp_f32_e64 v212, -v212
	v_sub_f32_e32 v234, v234, v213
	v_sub_f32_e32 v235, v235, v213
	v_sub_f32_e32 v236, v236, v213
	v_sub_f32_e32 v237, v237, v213
	v_sub_f32_e32 v238, v238, v213
	v_sub_f32_e32 v239, v239, v213
	v_sub_f32_e32 v240, v240, v213
	v_sub_f32_e32 v241, v241, v213
	v_sub_f32_e32 v242, v242, v213
	v_sub_f32_e32 v243, v243, v213
	v_sub_f32_e32 v244, v244, v213
	v_sub_f32_e32 v245, v245, v213
	v_sub_f32_e32 v246, v246, v213
	v_sub_f32_e32 v247, v247, v213
	v_sub_f32_e32 v248, v248, v213
	v_sub_f32_e32 v249, v249, v213
	v_sub_f32_e32 v82, v82, v213
	v_sub_f32_e32 v83, v83, v213
	v_sub_f32_e32 v84, v84, v213
	v_sub_f32_e32 v85, v85, v213
	v_sub_f32_e32 v86, v86, v213
	v_sub_f32_e32 v87, v87, v213
	v_sub_f32_e32 v88, v88, v213
	v_sub_f32_e32 v89, v89, v213
	v_sub_f32_e32 v90, v90, v213
	v_sub_f32_e32 v91, v91, v213
	v_sub_f32_e32 v92, v92, v213
	v_sub_f32_e32 v93, v93, v213
	v_sub_f32_e32 v94, v94, v213
	v_sub_f32_e32 v95, v95, v213
	v_sub_f32_e32 v96, v96, v213
	v_sub_f32_e32 v97, v97, v213
	v_pk_mul_f32 v[32:33], v[32:33], v[212:213] op_sel_hi:[1,0]
	v_pk_mul_f32 v[30:31], v[30:31], v[212:213] op_sel_hi:[1,0]
	v_pk_mul_f32 v[28:29], v[28:29], v[212:213] op_sel_hi:[1,0]
	v_pk_mul_f32 v[26:27], v[26:27], v[212:213] op_sel_hi:[1,0]
	v_pk_mul_f32 v[24:25], v[24:25], v[212:213] op_sel_hi:[1,0]
	v_pk_mul_f32 v[22:23], v[22:23], v[212:213] op_sel_hi:[1,0]
	v_pk_mul_f32 v[20:21], v[20:21], v[212:213] op_sel_hi:[1,0]
	v_pk_mul_f32 v[18:19], v[18:19], v[212:213] op_sel_hi:[1,0]
	v_pk_mul_f32 v[16:17], v[16:17], v[212:213] op_sel_hi:[1,0]
	v_pk_mul_f32 v[14:15], v[14:15], v[212:213] op_sel_hi:[1,0]
	v_pk_mul_f32 v[12:13], v[12:13], v[212:213] op_sel_hi:[1,0]
	v_pk_mul_f32 v[10:11], v[10:11], v[212:213] op_sel_hi:[1,0]
	v_pk_mul_f32 v[8:9], v[8:9], v[212:213] op_sel_hi:[1,0]
	v_pk_mul_f32 v[6:7], v[6:7], v[212:213] op_sel_hi:[1,0]
	v_pk_mul_f32 v[4:5], v[4:5], v[212:213] op_sel_hi:[1,0]
	v_pk_mul_f32 v[2:3], v[2:3], v[212:213] op_sel_hi:[1,0]
	v_mul_f32_e32 v209, v209, v212
	s_branch .LBB0_134
